# v74 + last K-loop DMA address adds folded (75 of 80 LDS-DMAs now SGPR-base; recycled bases kept in s[100:101])
# baseline (speedup 1.0000x reference)
.LBB0_267:
	s_add_i32 m0, s7, 0xc000
	ds_read_b128 v[160:163], v151
	ds_read_b128 v[164:167], v151 offset:1024
	ds_read_b128 v[168:171], v151 offset:2048
	ds_read_b128 v[172:175], v151 offset:3072
	ds_read_b128 v[176:179], v151 offset:4096
	ds_read_b128 v[180:183], v151 offset:5120
	ds_read_b128 v[184:187], v151 offset:6144
	ds_read_b128 v[190:193], v151 offset:7168
	global_load_lds_dwordx4 v138, s[4:5]
	s_add_i32 m0, s7, 0xe000
	s_nop 0
	global_load_lds_dwordx4 v140, s[4:5]
	s_waitcnt lgkmcnt(8)
	s_barrier
	s_waitcnt lgkmcnt(0)
	v_mfma_f32_16x16x32_bf16 v[126:129], v[142:145], v[160:163], v[126:129]
	v_mfma_f32_16x16x32_bf16 v[122:125], v[152:155], v[160:163], v[122:125]
	v_mfma_f32_16x16x32_bf16 v[110:113], v[142:145], v[168:171], v[110:113]
	v_mfma_f32_16x16x32_bf16 v[106:109], v[152:155], v[168:171], v[106:109]
	v_mfma_f32_16x16x32_bf16 v[94:97], v[142:145], v[176:179], v[94:97]
	v_mfma_f32_16x16x32_bf16 v[90:93], v[152:155], v[176:179], v[90:93]
	v_mfma_f32_16x16x32_bf16 v[78:81], v[142:145], v[184:187], v[78:81]
	v_mfma_f32_16x16x32_bf16 v[74:77], v[152:155], v[184:187], v[74:77]
	v_mfma_f32_16x16x32_bf16 v[126:129], v[146:149], v[164:167], v[126:129]
	v_mfma_f32_16x16x32_bf16 v[122:125], v[156:159], v[164:167], v[122:125]
	v_mfma_f32_16x16x32_bf16 v[110:113], v[146:149], v[172:175], v[110:113]
	v_mfma_f32_16x16x32_bf16 v[106:109], v[156:159], v[172:175], v[106:109]
	v_mfma_f32_16x16x32_bf16 v[94:97], v[146:149], v[180:183], v[94:97]
	v_mfma_f32_16x16x32_bf16 v[90:93], v[156:159], v[180:183], v[90:93]
	v_mfma_f32_16x16x32_bf16 v[78:81], v[146:149], v[190:193], v[78:81]
	v_mfma_f32_16x16x32_bf16 v[74:77], v[156:159], v[190:193], v[74:77]
	s_barrier
	s_add_i32 s88, 0, 0x14000
	s_add_i32 s86, s86, s22
	v_add_u32_e32 v0, s88, v150
	s_mov_b32 m0, s86
	ds_read_b128 v[194:197], v0
	ds_read_b128 v[198:201], v0 offset:1024
	ds_read_b128 v[202:205], v0 offset:2048
	ds_read_b128 v[206:209], v0 offset:3072
	global_load_lds_dwordx4 v134, s[12:13]
	s_add_i32 m0, s86, 0x2000
	s_nop 0
	global_load_lds_dwordx4 v130, s[12:13]
	s_barrier
	s_waitcnt lgkmcnt(0)
	v_mfma_f32_16x16x32_bf16 v[118:121], v[194:197], v[160:163], v[118:121]
	v_mfma_f32_16x16x32_bf16 v[114:117], v[202:205], v[160:163], v[114:117]
	v_mfma_f32_16x16x32_bf16 v[102:105], v[194:197], v[168:171], v[102:105]
	v_mfma_f32_16x16x32_bf16 v[98:101], v[202:205], v[168:171], v[98:101]
	v_mfma_f32_16x16x32_bf16 v[86:89], v[194:197], v[176:179], v[86:89]
	v_mfma_f32_16x16x32_bf16 v[82:85], v[202:205], v[176:179], v[82:85]
	v_mfma_f32_16x16x32_bf16 v[70:73], v[194:197], v[184:187], v[70:73]
	v_mfma_f32_16x16x32_bf16 v[66:69], v[202:205], v[184:187], v[66:69]
	v_mfma_f32_16x16x32_bf16 v[118:121], v[198:201], v[164:167], v[118:121]
	v_mfma_f32_16x16x32_bf16 v[114:117], v[206:209], v[164:167], v[114:117]
	v_mfma_f32_16x16x32_bf16 v[102:105], v[198:201], v[172:175], v[102:105]
	v_mfma_f32_16x16x32_bf16 v[98:101], v[206:209], v[172:175], v[98:101]
	v_mfma_f32_16x16x32_bf16 v[86:89], v[198:201], v[180:183], v[86:89]
	v_mfma_f32_16x16x32_bf16 v[82:85], v[206:209], v[180:183], v[82:85]
	v_mfma_f32_16x16x32_bf16 v[70:73], v[198:201], v[190:193], v[70:73]
	v_mfma_f32_16x16x32_bf16 v[66:69], v[206:209], v[190:193], v[66:69]
	s_mov_b32 m0, s7
	s_mov_b64 s[100:101], s[14:15]
	s_barrier
	ds_read_b128 v[160:163], v151 offset:16384
	ds_read_b128 v[164:167], v151 offset:17408
	ds_read_b128 v[168:171], v151 offset:18432
	ds_read_b128 v[172:175], v151 offset:19456
	ds_read_b128 v[176:179], v151 offset:20480
	ds_read_b128 v[180:183], v151 offset:21504
	ds_read_b128 v[184:187], v151 offset:22528
	ds_read_b128 v[190:193], v151 offset:23552
	global_load_lds_dwordx4 v136, s[100:101]
	s_mov_b32 m0, s23
	s_nop 0
	global_load_lds_dwordx4 v132, s[100:101]
	s_waitcnt vmcnt(10)
	s_barrier
	s_waitcnt lgkmcnt(0)
	v_mfma_f32_16x16x32_bf16 v[62:65], v[142:145], v[160:163], v[62:65]
	v_mfma_f32_16x16x32_bf16 v[58:61], v[152:155], v[160:163], v[58:61]
	v_mfma_f32_16x16x32_bf16 v[46:49], v[142:145], v[168:171], v[46:49]
	v_mfma_f32_16x16x32_bf16 v[42:45], v[152:155], v[168:171], v[42:45]
	v_mfma_f32_16x16x32_bf16 v[30:33], v[142:145], v[176:179], v[30:33]
	v_mfma_f32_16x16x32_bf16 v[26:29], v[152:155], v[176:179], v[26:29]
	v_mfma_f32_16x16x32_bf16 v[14:17], v[142:145], v[184:187], v[14:17]
	v_mfma_f32_16x16x32_bf16 v[10:13], v[152:155], v[184:187], v[10:13]
	v_mfma_f32_16x16x32_bf16 v[62:65], v[146:149], v[164:167], v[62:65]
	v_mfma_f32_16x16x32_bf16 v[58:61], v[156:159], v[164:167], v[58:61]
	v_mfma_f32_16x16x32_bf16 v[46:49], v[146:149], v[172:175], v[46:49]
	v_mfma_f32_16x16x32_bf16 v[42:45], v[156:159], v[172:175], v[42:45]
	v_mfma_f32_16x16x32_bf16 v[30:33], v[146:149], v[180:183], v[30:33]
	v_mfma_f32_16x16x32_bf16 v[26:29], v[156:159], v[180:183], v[26:29]
	v_mfma_f32_16x16x32_bf16 v[14:17], v[146:149], v[190:193], v[14:17]
	v_mfma_f32_16x16x32_bf16 v[10:13], v[156:159], v[190:193], v[10:13]
	s_barrier
	s_add_u32 s86, s12, 0x40000
	s_addc_u32 s87, s13, 0
	s_add_i32 s88, s88, s22
	s_mov_b32 m0, s88
	s_nop 0
	global_load_lds_dwordx4 v134, s[86:87]
	s_add_i32 m0, s88, 0x2000
	s_nop 0
	global_load_lds_dwordx4 v130, s[86:87]
	s_add_i32 s86, 0, 0x18000
	v_add_u32_e32 v0, s86, v150
	ds_read_b128 v[142:145], v0
	ds_read_b128 v[146:149], v0 offset:1024
	ds_read_b128 v[152:155], v0 offset:2048
	ds_read_b128 v[156:159], v0 offset:3072
	s_waitcnt vmcnt(6)
	s_barrier
	v_mfma_f32_16x16x32_bf16 v[54:57], v[194:197], v[160:163], v[54:57]
	v_mfma_f32_16x16x32_bf16 v[50:53], v[202:205], v[160:163], v[50:53]
	v_mfma_f32_16x16x32_bf16 v[38:41], v[194:197], v[168:171], v[38:41]
	v_mfma_f32_16x16x32_bf16 v[34:37], v[202:205], v[168:171], v[34:37]
	v_mfma_f32_16x16x32_bf16 v[22:25], v[194:197], v[176:179], v[22:25]
	v_mfma_f32_16x16x32_bf16 v[18:21], v[202:205], v[176:179], v[18:21]
	v_mfma_f32_16x16x32_bf16 v[6:9], v[194:197], v[184:187], v[6:9]
	v_mfma_f32_16x16x32_bf16 v[2:5], v[202:205], v[184:187], v[2:5]
	v_mfma_f32_16x16x32_bf16 v[54:57], v[198:201], v[164:167], v[54:57]
	v_mfma_f32_16x16x32_bf16 v[50:53], v[206:209], v[164:167], v[50:53]
	v_mfma_f32_16x16x32_bf16 v[38:41], v[198:201], v[172:175], v[38:41]
	v_mfma_f32_16x16x32_bf16 v[34:37], v[206:209], v[172:175], v[34:37]
	v_mfma_f32_16x16x32_bf16 v[22:25], v[198:201], v[180:183], v[22:25]
	v_mfma_f32_16x16x32_bf16 v[18:21], v[206:209], v[180:183], v[18:21]
	v_mfma_f32_16x16x32_bf16 v[6:9], v[198:201], v[190:193], v[6:9]
	v_mfma_f32_16x16x32_bf16 v[2:5], v[206:209], v[190:193], v[2:5]
	s_barrier
	s_add_u32 s14, s14, 0x40000
	s_addc_u32 s15, s15, 0
	s_mov_b32 m0, s28
	ds_read_b128 v[160:163], v151 offset:32768
	ds_read_b128 v[164:167], v151 offset:33792
	ds_read_b128 v[168:171], v151 offset:34816
	ds_read_b128 v[172:175], v151 offset:35840
	ds_read_b128 v[176:179], v151 offset:36864
	ds_read_b128 v[180:183], v151 offset:37888
	ds_read_b128 v[184:187], v151 offset:38912
	ds_read_b128 v[190:193], v151 offset:39936
	global_load_lds_dwordx4 v136, s[14:15]
	s_mov_b32 m0, s29
	s_nop 0
	global_load_lds_dwordx4 v132, s[14:15]
	s_waitcnt lgkmcnt(8)
	s_barrier
	s_waitcnt lgkmcnt(0)
	v_mfma_f32_16x16x32_bf16 v[126:129], v[142:145], v[160:163], v[126:129]
	v_mfma_f32_16x16x32_bf16 v[122:125], v[152:155], v[160:163], v[122:125]
	v_mfma_f32_16x16x32_bf16 v[110:113], v[142:145], v[168:171], v[110:113]
	v_mfma_f32_16x16x32_bf16 v[106:109], v[152:155], v[168:171], v[106:109]
	v_mfma_f32_16x16x32_bf16 v[94:97], v[142:145], v[176:179], v[94:97]
	v_mfma_f32_16x16x32_bf16 v[90:93], v[152:155], v[176:179], v[90:93]
	v_mfma_f32_16x16x32_bf16 v[78:81], v[142:145], v[184:187], v[78:81]
	v_mfma_f32_16x16x32_bf16 v[74:77], v[152:155], v[184:187], v[74:77]
	v_mfma_f32_16x16x32_bf16 v[126:129], v[146:149], v[164:167], v[126:129]
	v_mfma_f32_16x16x32_bf16 v[122:125], v[156:159], v[164:167], v[122:125]
	v_mfma_f32_16x16x32_bf16 v[110:113], v[146:149], v[172:175], v[110:113]
	v_mfma_f32_16x16x32_bf16 v[106:109], v[156:159], v[172:175], v[106:109]
	v_mfma_f32_16x16x32_bf16 v[94:97], v[146:149], v[180:183], v[94:97]
	v_mfma_f32_16x16x32_bf16 v[90:93], v[156:159], v[180:183], v[90:93]
	v_mfma_f32_16x16x32_bf16 v[78:81], v[146:149], v[190:193], v[78:81]
	v_mfma_f32_16x16x32_bf16 v[74:77], v[156:159], v[190:193], v[74:77]
	s_barrier
	s_add_i32 s14, 0, 0x1c000
	s_add_i32 s15, s86, s22
	v_add_u32_e32 v0, s14, v150
	s_mov_b32 m0, s15
	ds_read_b128 v[194:197], v0
	ds_read_b128 v[198:201], v0 offset:1024
	ds_read_b128 v[202:205], v0 offset:2048
	ds_read_b128 v[206:209], v0 offset:3072
	s_add_u32 s98, s12, s40
	s_addc_u32 s99, s13, s41
	global_load_lds_dwordx4 v134, s[98:99]
	s_add_i32 m0, s15, 0x2000
	s_add_u32 s98, s12, s40
	s_addc_u32 s99, s13, s41
	global_load_lds_dwordx4 v130, s[98:99]
	s_barrier
	s_waitcnt lgkmcnt(0)
	v_mfma_f32_16x16x32_bf16 v[118:121], v[194:197], v[160:163], v[118:121]
	v_mfma_f32_16x16x32_bf16 v[114:117], v[202:205], v[160:163], v[114:117]
	v_mfma_f32_16x16x32_bf16 v[102:105], v[194:197], v[168:171], v[102:105]
	v_mfma_f32_16x16x32_bf16 v[98:101], v[202:205], v[168:171], v[98:101]
	v_mfma_f32_16x16x32_bf16 v[86:89], v[194:197], v[176:179], v[86:89]
	v_mfma_f32_16x16x32_bf16 v[82:85], v[202:205], v[176:179], v[82:85]
	v_mfma_f32_16x16x32_bf16 v[70:73], v[194:197], v[184:187], v[70:73]
	v_mfma_f32_16x16x32_bf16 v[66:69], v[202:205], v[184:187], v[66:69]
	v_mfma_f32_16x16x32_bf16 v[118:121], v[198:201], v[164:167], v[118:121]
	v_mfma_f32_16x16x32_bf16 v[114:117], v[206:209], v[164:167], v[114:117]
	v_mfma_f32_16x16x32_bf16 v[102:105], v[198:201], v[172:175], v[102:105]
	v_mfma_f32_16x16x32_bf16 v[98:101], v[206:209], v[172:175], v[98:101]
	v_mfma_f32_16x16x32_bf16 v[86:89], v[198:201], v[180:183], v[86:89]
	v_mfma_f32_16x16x32_bf16 v[82:85], v[206:209], v[180:183], v[82:85]
	v_mfma_f32_16x16x32_bf16 v[70:73], v[198:201], v[190:193], v[70:73]
	v_mfma_f32_16x16x32_bf16 v[66:69], v[206:209], v[190:193], v[66:69]
	s_mov_b32 m0, s38
	s_barrier
	ds_read_b128 v[160:163], v151 offset:49152
	ds_read_b128 v[164:167], v151 offset:50176
	ds_read_b128 v[168:171], v151 offset:51200
	ds_read_b128 v[172:175], v151 offset:52224
	ds_read_b128 v[176:179], v151 offset:53248
	ds_read_b128 v[180:183], v151 offset:54272
	ds_read_b128 v[184:187], v151 offset:55296
	ds_read_b128 v[190:193], v151 offset:56320
	s_add_u32 s98, s100, s40
	s_addc_u32 s99, s101, s41
	global_load_lds_dwordx4 v136, s[98:99]
	s_mov_b32 m0, s39
	s_add_u32 s98, s100, s40
	s_addc_u32 s99, s101, s41
	global_load_lds_dwordx4 v132, s[98:99]
	s_waitcnt vmcnt(10)
	s_barrier
	s_waitcnt lgkmcnt(0)
	v_mfma_f32_16x16x32_bf16 v[62:65], v[142:145], v[160:163], v[62:65]
	v_mfma_f32_16x16x32_bf16 v[58:61], v[152:155], v[160:163], v[58:61]
	v_mfma_f32_16x16x32_bf16 v[46:49], v[142:145], v[168:171], v[46:49]
	v_mfma_f32_16x16x32_bf16 v[42:45], v[152:155], v[168:171], v[42:45]
	v_mfma_f32_16x16x32_bf16 v[30:33], v[142:145], v[176:179], v[30:33]
	v_mfma_f32_16x16x32_bf16 v[26:29], v[152:155], v[176:179], v[26:29]
	v_mfma_f32_16x16x32_bf16 v[14:17], v[142:145], v[184:187], v[14:17]
	v_mfma_f32_16x16x32_bf16 v[10:13], v[152:155], v[184:187], v[10:13]
	v_mfma_f32_16x16x32_bf16 v[62:65], v[146:149], v[164:167], v[62:65]
	v_mfma_f32_16x16x32_bf16 v[58:61], v[156:159], v[164:167], v[58:61]
	v_mfma_f32_16x16x32_bf16 v[46:49], v[146:149], v[172:175], v[46:49]
	v_mfma_f32_16x16x32_bf16 v[42:45], v[156:159], v[172:175], v[42:45]
	v_mfma_f32_16x16x32_bf16 v[30:33], v[146:149], v[180:183], v[30:33]
	v_mfma_f32_16x16x32_bf16 v[26:29], v[156:159], v[180:183], v[26:29]
	v_mfma_f32_16x16x32_bf16 v[14:17], v[146:149], v[190:193], v[14:17]
	v_mfma_f32_16x16x32_bf16 v[10:13], v[156:159], v[190:193], v[10:13]
	s_barrier
	s_add_u32 s12, s12, 0x40080
	s_addc_u32 s13, s13, 0
	s_add_i32 s14, s14, s22
	s_mov_b32 m0, s14
	s_nop 0
	global_load_lds_dwordx4 v134, s[12:13]
	s_add_i32 m0, s14, 0x2000
	s_nop 0
	global_load_lds_dwordx4 v130, s[12:13]
	s_add_i32 s86, 0, 0x10000
	v_add_u32_e32 v0, s86, v150
	ds_read_b128 v[142:145], v0
	ds_read_b128 v[146:149], v0 offset:1024
	ds_read_b128 v[152:155], v0 offset:2048
	ds_read_b128 v[156:159], v0 offset:3072
	s_waitcnt vmcnt(6)
	s_barrier
	v_mfma_f32_16x16x32_bf16 v[54:57], v[194:197], v[160:163], v[54:57]
	v_mfma_f32_16x16x32_bf16 v[50:53], v[202:205], v[160:163], v[50:53]
	v_mfma_f32_16x16x32_bf16 v[38:41], v[194:197], v[168:171], v[38:41]
	v_mfma_f32_16x16x32_bf16 v[34:37], v[202:205], v[168:171], v[34:37]
	v_mfma_f32_16x16x32_bf16 v[22:25], v[194:197], v[176:179], v[22:25]
	v_mfma_f32_16x16x32_bf16 v[18:21], v[202:205], v[176:179], v[18:21]
	v_mfma_f32_16x16x32_bf16 v[6:9], v[194:197], v[184:187], v[6:9]
	v_mfma_f32_16x16x32_bf16 v[2:5], v[202:205], v[184:187], v[2:5]
	v_mfma_f32_16x16x32_bf16 v[54:57], v[198:201], v[164:167], v[54:57]
	v_mfma_f32_16x16x32_bf16 v[50:53], v[206:209], v[164:167], v[50:53]
	v_mfma_f32_16x16x32_bf16 v[38:41], v[198:201], v[172:175], v[38:41]
	v_mfma_f32_16x16x32_bf16 v[34:37], v[206:209], v[172:175], v[34:37]
	v_mfma_f32_16x16x32_bf16 v[22:25], v[198:201], v[180:183], v[22:25]
	v_mfma_f32_16x16x32_bf16 v[18:21], v[206:209], v[180:183], v[18:21]
	v_mfma_f32_16x16x32_bf16 v[6:9], v[198:201], v[190:193], v[6:9]
	v_mfma_f32_16x16x32_bf16 v[2:5], v[206:209], v[190:193], v[2:5]
	s_add_i32 s85, s85, 2
	s_add_u32 s4, s4, 0x100
	s_addc_u32 s5, s5, 0
	s_add_u32 s78, s78, 0x100
	s_addc_u32 s79, s79, 0
	s_add_u32 s12, s4, 0xfffc0080
	s_addc_u32 s13, s5, -1
	s_cmp_eq_u32 s85, 12
	s_cselect_b32 s15, s44, s13
	s_cselect_b32 s14, s45, s12
	s_cselect_b32 s13, s47, s79
	s_cselect_b32 s12, s55, s78
	s_cmp_gt_u32 s85, 13
	s_barrier
	s_cbranch_scc0 .LBB0_267
	s_waitcnt lgkmcnt(0)
	v_mov_b32_e32 v156, v252
	s_mov_b64 s[4:5], -1
	v_and_b32_e32 v154, 63, v156
	s_andn2_b64 vcc, exec, s[2:3]
	v_lshlrev_b32_e32 v142, 2, v154
	s_cbranch_vccnz .LBB0_270
	v_lshlrev_b32_e32 v155, 2, v154
	s_mov_b64 s[4:5], 0

.LBB0_919:
	s_add_i32 m0, s43, 0xc000
	ds_read_b128 v[146:149], v253
	ds_read_b128 v[150:153], v253 offset:1024
	ds_read_b128 v[168:171], v253 offset:2048
	ds_read_b128 v[172:175], v253 offset:3072
	ds_read_b128 v[176:179], v253 offset:4096
	ds_read_b128 v[180:183], v253 offset:5120
	ds_read_b128 v[184:187], v253 offset:6144
	ds_read_b128 v[190:193], v253 offset:7168
	global_load_lds_dwordx4 v164, s[6:7]
	s_add_i32 m0, s43, 0xe000
	v_lshl_add_u64 v[154:155], s[6:7], 0, v[166:167]
	global_load_lds_dwordx4 v[154:155], off
	s_waitcnt lgkmcnt(8)
	s_barrier
	s_waitcnt lgkmcnt(0)
	v_mfma_f32_16x16x32_bf16 v[126:129], v[130:133], v[146:149], v[126:129]
	v_mfma_f32_16x16x32_bf16 v[70:73], v[138:141], v[146:149], v[70:73]
	v_mfma_f32_16x16x32_bf16 v[122:125], v[130:133], v[168:171], v[122:125]
	v_mfma_f32_16x16x32_bf16 v[74:77], v[138:141], v[168:171], v[74:77]
	v_mfma_f32_16x16x32_bf16 v[114:117], v[130:133], v[176:179], v[114:117]
	v_mfma_f32_16x16x32_bf16 v[66:69], v[138:141], v[176:179], v[66:69]
	v_mfma_f32_16x16x32_bf16 v[110:113], v[130:133], v[184:187], v[110:113]
	v_mfma_f32_16x16x32_bf16 v[78:81], v[138:141], v[184:187], v[78:81]
	v_mfma_f32_16x16x32_bf16 v[126:129], v[134:137], v[150:153], v[126:129]
	v_mfma_f32_16x16x32_bf16 v[70:73], v[142:145], v[150:153], v[70:73]
	v_mfma_f32_16x16x32_bf16 v[122:125], v[134:137], v[172:175], v[122:125]
	v_mfma_f32_16x16x32_bf16 v[74:77], v[142:145], v[172:175], v[74:77]
	v_mfma_f32_16x16x32_bf16 v[114:117], v[134:137], v[180:183], v[114:117]
	v_mfma_f32_16x16x32_bf16 v[66:69], v[142:145], v[180:183], v[66:69]
	v_mfma_f32_16x16x32_bf16 v[110:113], v[134:137], v[190:193], v[110:113]
	v_mfma_f32_16x16x32_bf16 v[78:81], v[142:145], v[190:193], v[78:81]
	s_barrier
	s_add_i32 vcc_hi, 0, 0x14000
	s_add_i32 s6, vcc_lo, s39
	v_add_u32_e32 v0, vcc_hi, v254
	s_mov_b32 m0, s6
	ds_read_b128 v[194:197], v0
	ds_read_b128 v[198:201], v0 offset:1024
	ds_read_b128 v[202:205], v0 offset:2048
	ds_read_b128 v[206:209], v0 offset:3072
	global_load_lds_dwordx4 v160, s[90:91]
	s_add_i32 m0, s6, 0x2000
	s_nop 0
	global_load_lds_dwordx4 v156, s[90:91]
	s_barrier
	s_waitcnt lgkmcnt(0)
	v_mfma_f32_16x16x32_bf16 v[118:121], v[194:197], v[146:149], v[118:121]
	v_mfma_f32_16x16x32_bf16 v[94:97], v[202:205], v[146:149], v[94:97]
	v_mfma_f32_16x16x32_bf16 v[106:109], v[194:197], v[168:171], v[106:109]
	v_mfma_f32_16x16x32_bf16 v[90:93], v[202:205], v[168:171], v[90:93]
	v_mfma_f32_16x16x32_bf16 v[102:105], v[194:197], v[176:179], v[102:105]
	v_mfma_f32_16x16x32_bf16 v[82:85], v[202:205], v[176:179], v[82:85]
	v_mfma_f32_16x16x32_bf16 v[98:101], v[194:197], v[184:187], v[98:101]
	v_mfma_f32_16x16x32_bf16 v[86:89], v[202:205], v[184:187], v[86:89]
	v_mfma_f32_16x16x32_bf16 v[118:121], v[198:201], v[150:153], v[118:121]
	v_mfma_f32_16x16x32_bf16 v[94:97], v[206:209], v[150:153], v[94:97]
	v_mfma_f32_16x16x32_bf16 v[106:109], v[198:201], v[172:175], v[106:109]
	v_mfma_f32_16x16x32_bf16 v[90:93], v[206:209], v[172:175], v[90:93]
	v_mfma_f32_16x16x32_bf16 v[102:105], v[198:201], v[180:183], v[102:105]
	v_mfma_f32_16x16x32_bf16 v[82:85], v[206:209], v[180:183], v[82:85]
	v_mfma_f32_16x16x32_bf16 v[98:101], v[198:201], v[190:193], v[98:101]
	v_mfma_f32_16x16x32_bf16 v[86:89], v[206:209], v[190:193], v[86:89]
	s_mov_b32 m0, s43
	s_mov_b64 s[100:101], s[92:93]
	s_barrier
	ds_read_b128 v[146:149], v253 offset:16384
	ds_read_b128 v[150:153], v253 offset:17408
	ds_read_b128 v[168:171], v253 offset:18432
	ds_read_b128 v[172:175], v253 offset:19456
	ds_read_b128 v[176:179], v253 offset:20480
	ds_read_b128 v[180:183], v253 offset:21504
	ds_read_b128 v[184:187], v253 offset:22528
	ds_read_b128 v[190:193], v253 offset:23552
	global_load_lds_dwordx4 v162, s[100:101]
	s_mov_b32 m0, s60
	s_nop 0
	global_load_lds_dwordx4 v158, s[100:101]
	s_waitcnt vmcnt(10)
	s_barrier
	s_waitcnt lgkmcnt(0)
	v_mfma_f32_16x16x32_bf16 v[62:65], v[130:133], v[146:149], v[62:65]
	v_mfma_f32_16x16x32_bf16 v[10:13], v[138:141], v[146:149], v[10:13]
	v_mfma_f32_16x16x32_bf16 v[58:61], v[130:133], v[168:171], v[58:61]
	v_mfma_f32_16x16x32_bf16 v[14:17], v[138:141], v[168:171], v[14:17]
	v_mfma_f32_16x16x32_bf16 v[54:57], v[130:133], v[176:179], v[54:57]
	v_mfma_f32_16x16x32_bf16 v[6:9], v[138:141], v[176:179], v[6:9]
	v_mfma_f32_16x16x32_bf16 v[42:45], v[130:133], v[184:187], v[42:45]
	v_mfma_f32_16x16x32_bf16 v[2:5], v[138:141], v[184:187], v[2:5]
	v_mfma_f32_16x16x32_bf16 v[62:65], v[134:137], v[150:153], v[62:65]
	v_mfma_f32_16x16x32_bf16 v[10:13], v[142:145], v[150:153], v[10:13]
	v_mfma_f32_16x16x32_bf16 v[58:61], v[134:137], v[172:175], v[58:61]
	v_mfma_f32_16x16x32_bf16 v[14:17], v[142:145], v[172:175], v[14:17]
	v_mfma_f32_16x16x32_bf16 v[54:57], v[134:137], v[180:183], v[54:57]
	v_mfma_f32_16x16x32_bf16 v[6:9], v[142:145], v[180:183], v[6:9]
	v_mfma_f32_16x16x32_bf16 v[42:45], v[134:137], v[190:193], v[42:45]
	v_mfma_f32_16x16x32_bf16 v[2:5], v[142:145], v[190:193], v[2:5]
	s_barrier
	s_add_u32 s6, s90, 0x40000
	s_addc_u32 s7, s91, 0
	s_add_i32 vcc_lo, vcc_hi, s39
	s_mov_b32 m0, vcc_lo
	s_nop 0
	global_load_lds_dwordx4 v160, s[6:7]
	s_add_i32 m0, vcc_lo, 0x2000
	s_nop 0
	global_load_lds_dwordx4 v156, s[6:7]
	s_add_i32 vcc_lo, 0, 0x18000
	v_add_u32_e32 v0, vcc_lo, v254
	ds_read_b128 v[130:133], v0
	ds_read_b128 v[134:137], v0 offset:1024
	ds_read_b128 v[138:141], v0 offset:2048
	ds_read_b128 v[142:145], v0 offset:3072
	s_waitcnt vmcnt(6)
	s_barrier
	v_mfma_f32_16x16x32_bf16 v[50:53], v[194:197], v[146:149], v[50:53]
	v_mfma_f32_16x16x32_bf16 v[26:29], v[202:205], v[146:149], v[26:29]
	v_mfma_f32_16x16x32_bf16 v[46:49], v[194:197], v[168:171], v[46:49]
	v_mfma_f32_16x16x32_bf16 v[30:33], v[202:205], v[168:171], v[30:33]
	v_mfma_f32_16x16x32_bf16 v[38:41], v[194:197], v[176:179], v[38:41]
	v_mfma_f32_16x16x32_bf16 v[22:25], v[202:205], v[176:179], v[22:25]
	v_mfma_f32_16x16x32_bf16 v[34:37], v[194:197], v[184:187], v[34:37]
	v_mfma_f32_16x16x32_bf16 v[18:21], v[202:205], v[184:187], v[18:21]
	v_mfma_f32_16x16x32_bf16 v[50:53], v[198:201], v[150:153], v[50:53]
	v_mfma_f32_16x16x32_bf16 v[26:29], v[206:209], v[150:153], v[26:29]
	v_mfma_f32_16x16x32_bf16 v[46:49], v[198:201], v[172:175], v[46:49]
	v_mfma_f32_16x16x32_bf16 v[30:33], v[206:209], v[172:175], v[30:33]
	v_mfma_f32_16x16x32_bf16 v[38:41], v[198:201], v[180:183], v[38:41]
	v_mfma_f32_16x16x32_bf16 v[22:25], v[206:209], v[180:183], v[22:25]
	v_mfma_f32_16x16x32_bf16 v[34:37], v[198:201], v[190:193], v[34:37]
	v_mfma_f32_16x16x32_bf16 v[18:21], v[206:209], v[190:193], v[18:21]
	s_barrier
	s_add_u32 s6, s92, 0x40000
	s_addc_u32 s7, s93, 0
	s_mov_b32 m0, s61
	ds_read_b128 v[146:149], v253 offset:32768
	ds_read_b128 v[150:153], v253 offset:33792
	ds_read_b128 v[168:171], v253 offset:34816
	ds_read_b128 v[172:175], v253 offset:35840
	ds_read_b128 v[176:179], v253 offset:36864
	ds_read_b128 v[180:183], v253 offset:37888
	ds_read_b128 v[184:187], v253 offset:38912
	ds_read_b128 v[190:193], v253 offset:39936
	global_load_lds_dwordx4 v162, s[6:7]
	s_mov_b32 m0, s72
	s_nop 0
	global_load_lds_dwordx4 v158, s[6:7]
	s_waitcnt lgkmcnt(8)
	s_barrier
	s_waitcnt lgkmcnt(0)
	v_mfma_f32_16x16x32_bf16 v[126:129], v[130:133], v[146:149], v[126:129]
	v_mfma_f32_16x16x32_bf16 v[70:73], v[138:141], v[146:149], v[70:73]
	v_mfma_f32_16x16x32_bf16 v[122:125], v[130:133], v[168:171], v[122:125]
	v_mfma_f32_16x16x32_bf16 v[74:77], v[138:141], v[168:171], v[74:77]
	v_mfma_f32_16x16x32_bf16 v[114:117], v[130:133], v[176:179], v[114:117]
	v_mfma_f32_16x16x32_bf16 v[66:69], v[138:141], v[176:179], v[66:69]
	v_mfma_f32_16x16x32_bf16 v[110:113], v[130:133], v[184:187], v[110:113]
	v_mfma_f32_16x16x32_bf16 v[78:81], v[138:141], v[184:187], v[78:81]
	v_mfma_f32_16x16x32_bf16 v[126:129], v[134:137], v[150:153], v[126:129]
	v_mfma_f32_16x16x32_bf16 v[70:73], v[142:145], v[150:153], v[70:73]
	v_mfma_f32_16x16x32_bf16 v[122:125], v[134:137], v[172:175], v[122:125]
	v_mfma_f32_16x16x32_bf16 v[74:77], v[142:145], v[172:175], v[74:77]
	v_mfma_f32_16x16x32_bf16 v[114:117], v[134:137], v[180:183], v[114:117]
	v_mfma_f32_16x16x32_bf16 v[66:69], v[142:145], v[180:183], v[66:69]
	v_mfma_f32_16x16x32_bf16 v[110:113], v[134:137], v[190:193], v[110:113]
	v_mfma_f32_16x16x32_bf16 v[78:81], v[142:145], v[190:193], v[78:81]
	s_barrier
	s_add_i32 s92, 0, 0x1c000
	s_add_i32 s6, vcc_lo, s39
	v_add_u32_e32 v0, s92, v254
	s_mov_b32 m0, s6
	ds_read_b128 v[194:197], v0
	ds_read_b128 v[198:201], v0 offset:1024
	ds_read_b128 v[202:205], v0 offset:2048
	ds_read_b128 v[206:209], v0 offset:3072
	s_add_u32 s98, s90, s40
	s_addc_u32 s99, s91, s41
	global_load_lds_dwordx4 v160, s[98:99]
	s_add_i32 m0, s6, 0x2000
	s_add_u32 s98, s90, s40
	s_addc_u32 s99, s91, s41
	global_load_lds_dwordx4 v156, s[98:99]
	s_barrier
	s_waitcnt lgkmcnt(0)
	v_mfma_f32_16x16x32_bf16 v[118:121], v[194:197], v[146:149], v[118:121]
	v_mfma_f32_16x16x32_bf16 v[94:97], v[202:205], v[146:149], v[94:97]
	v_mfma_f32_16x16x32_bf16 v[106:109], v[194:197], v[168:171], v[106:109]
	v_mfma_f32_16x16x32_bf16 v[90:93], v[202:205], v[168:171], v[90:93]
	v_mfma_f32_16x16x32_bf16 v[102:105], v[194:197], v[176:179], v[102:105]
	v_mfma_f32_16x16x32_bf16 v[82:85], v[202:205], v[176:179], v[82:85]
	v_mfma_f32_16x16x32_bf16 v[98:101], v[194:197], v[184:187], v[98:101]
	v_mfma_f32_16x16x32_bf16 v[86:89], v[202:205], v[184:187], v[86:89]
	v_mfma_f32_16x16x32_bf16 v[118:121], v[198:201], v[150:153], v[118:121]
	v_mfma_f32_16x16x32_bf16 v[94:97], v[206:209], v[150:153], v[94:97]
	v_mfma_f32_16x16x32_bf16 v[106:109], v[198:201], v[172:175], v[106:109]
	v_mfma_f32_16x16x32_bf16 v[90:93], v[206:209], v[172:175], v[90:93]
	v_mfma_f32_16x16x32_bf16 v[102:105], v[198:201], v[180:183], v[102:105]
	v_mfma_f32_16x16x32_bf16 v[82:85], v[206:209], v[180:183], v[82:85]
	v_mfma_f32_16x16x32_bf16 v[98:101], v[198:201], v[190:193], v[98:101]
	v_mfma_f32_16x16x32_bf16 v[86:89], v[206:209], v[190:193], v[86:89]
	s_mov_b32 m0, s95
	s_barrier
	ds_read_b128 v[146:149], v253 offset:49152
	ds_read_b128 v[150:153], v253 offset:50176
	ds_read_b128 v[168:171], v253 offset:51200
	ds_read_b128 v[172:175], v253 offset:52224
	ds_read_b128 v[176:179], v253 offset:53248
	ds_read_b128 v[180:183], v253 offset:54272
	ds_read_b128 v[184:187], v253 offset:55296
	ds_read_b128 v[190:193], v253 offset:56320
	s_add_u32 s98, s100, s40
	s_addc_u32 s99, s101, s41
	global_load_lds_dwordx4 v162, s[98:99]
	s_mov_b32 m0, s96
	s_add_u32 s98, s100, s40
	s_addc_u32 s99, s101, s41
	global_load_lds_dwordx4 v158, s[98:99]
	s_waitcnt vmcnt(10)
	s_barrier
	s_waitcnt lgkmcnt(0)
	v_mfma_f32_16x16x32_bf16 v[62:65], v[130:133], v[146:149], v[62:65]
	v_mfma_f32_16x16x32_bf16 v[10:13], v[138:141], v[146:149], v[10:13]
	v_mfma_f32_16x16x32_bf16 v[58:61], v[130:133], v[168:171], v[58:61]
	v_mfma_f32_16x16x32_bf16 v[14:17], v[138:141], v[168:171], v[14:17]
	v_mfma_f32_16x16x32_bf16 v[54:57], v[130:133], v[176:179], v[54:57]
	v_mfma_f32_16x16x32_bf16 v[6:9], v[138:141], v[176:179], v[6:9]
	v_mfma_f32_16x16x32_bf16 v[42:45], v[130:133], v[184:187], v[42:45]
	v_mfma_f32_16x16x32_bf16 v[2:5], v[138:141], v[184:187], v[2:5]
	v_mfma_f32_16x16x32_bf16 v[62:65], v[134:137], v[150:153], v[62:65]
	v_mfma_f32_16x16x32_bf16 v[10:13], v[142:145], v[150:153], v[10:13]
	v_mfma_f32_16x16x32_bf16 v[58:61], v[134:137], v[172:175], v[58:61]
	v_mfma_f32_16x16x32_bf16 v[14:17], v[142:145], v[172:175], v[14:17]
	v_mfma_f32_16x16x32_bf16 v[54:57], v[134:137], v[180:183], v[54:57]
	v_mfma_f32_16x16x32_bf16 v[6:9], v[142:145], v[180:183], v[6:9]
	v_mfma_f32_16x16x32_bf16 v[42:45], v[134:137], v[190:193], v[42:45]
	v_mfma_f32_16x16x32_bf16 v[2:5], v[142:145], v[190:193], v[2:5]
	s_barrier
	s_add_u32 s6, s90, 0x40080
	s_addc_u32 s7, s91, 0
	s_add_i32 s90, s92, s39
	s_mov_b32 m0, s90
	s_nop 0
	global_load_lds_dwordx4 v160, s[6:7]
	s_add_i32 m0, s90, 0x2000
	s_nop 0
	global_load_lds_dwordx4 v156, s[6:7]
	s_add_i32 vcc_lo, 0, 0x10000
	v_add_u32_e32 v0, vcc_lo, v254
	ds_read_b128 v[130:133], v0
	ds_read_b128 v[134:137], v0 offset:1024
	ds_read_b128 v[138:141], v0 offset:2048
	ds_read_b128 v[142:145], v0 offset:3072
	s_waitcnt vmcnt(6)
	s_barrier
	v_mfma_f32_16x16x32_bf16 v[50:53], v[194:197], v[146:149], v[50:53]
	v_mfma_f32_16x16x32_bf16 v[26:29], v[202:205], v[146:149], v[26:29]
	v_mfma_f32_16x16x32_bf16 v[46:49], v[194:197], v[168:171], v[46:49]
	v_mfma_f32_16x16x32_bf16 v[30:33], v[202:205], v[168:171], v[30:33]
	v_mfma_f32_16x16x32_bf16 v[38:41], v[194:197], v[176:179], v[38:41]
	v_mfma_f32_16x16x32_bf16 v[22:25], v[202:205], v[176:179], v[22:25]
	v_mfma_f32_16x16x32_bf16 v[34:37], v[194:197], v[184:187], v[34:37]
	v_mfma_f32_16x16x32_bf16 v[18:21], v[202:205], v[184:187], v[18:21]
	v_mfma_f32_16x16x32_bf16 v[50:53], v[198:201], v[150:153], v[50:53]
	v_mfma_f32_16x16x32_bf16 v[26:29], v[206:209], v[150:153], v[26:29]
	v_mfma_f32_16x16x32_bf16 v[46:49], v[198:201], v[172:175], v[46:49]
	v_mfma_f32_16x16x32_bf16 v[30:33], v[206:209], v[172:175], v[30:33]
	v_mfma_f32_16x16x32_bf16 v[38:41], v[198:201], v[180:183], v[38:41]
	v_mfma_f32_16x16x32_bf16 v[22:25], v[206:209], v[180:183], v[22:25]
	v_mfma_f32_16x16x32_bf16 v[34:37], v[198:201], v[190:193], v[34:37]
	v_mfma_f32_16x16x32_bf16 v[18:21], v[206:209], v[190:193], v[18:21]
	s_add_i32 s45, s45, 2
	s_add_u32 s28, s28, 0x100
	s_addc_u32 s29, s29, 0
	s_mov_b64 s[6:7], s[88:89]
	s_add_u32 s88, s6, 0x100
	s_addc_u32 s89, s7, 0
	s_cmp_eq_u32 s45, 12
	s_cselect_b32 s93, s17, s89
	s_cselect_b32 s92, s22, s88
	s_cselect_b32 s91, s15, s29
	s_cselect_b32 s90, s23, s28
	s_cmp_gt_u32 s45, 13
	s_barrier
	s_cbranch_scc0 .LBB0_919
	s_waitcnt lgkmcnt(0)
	v_mov_b32_e32 v131, v252
	s_lshl_b32 s88, s5, 7
	v_bfe_u32 v130, v131, 4, 2
	v_and_b32_e32 v134, 15, v131
	v_lshlrev_b32_e32 v0, 4, v130
	s_ashr_i32 s89, s88, 31
	s_lshl_b32 s15, s4, 8
	v_or3_b32 v135, v0, s97, v134
	s_lshl_b64 s[4:5], s[88:89], 2
	v_lshrrev_b32_e32 v140, 1, v135
	s_add_u32 s4, s73, s4
	s_addc_u32 s5, s74, s5
	v_lshlrev_b32_e32 v0, 2, v140
	v_and_b32_e32 v144, 1, v131
	v_lshl_add_u64 v[132:133], s[4:5], 0, v[0:1]
	v_cmp_eq_u32_e32 vcc, 1, v144
	v_mov_b32_e32 v0, 0xb00
	s_movk_i32 s4, 0x5000
	v_cndmask_b32_e32 v141, 0, v0, vcc
	v_lshlrev_b32_e32 v0, 2, v141
	v_lshl_add_u64 v[132:133], v[132:133], 0, v[0:1]
	v_add_co_u32_e32 v138, vcc, s4, v132
	s_mov_b32 s4, 0xb000
	s_nop 0
	v_addc_co_u32_e32 v139, vcc, 0, v133, vcc
	global_load_dword v136, v[132:133], off
	global_load_dword v137, v[138:139], off offset:2048
	v_add_co_u32_e32 v132, vcc, s4, v132
	v_add_u32_e32 v0, s88, v141
	s_nop 0
	v_addc_co_u32_e32 v133, vcc, 0, v133, vcc
	global_load_dword v138, v[132:133], off
	v_or_b32_e32 v132, v140, v0
	v_ashrrev_i32_e32 v133, 31, v132
	v_lshl_add_u64 v[132:133], v[132:133], 2, s[12:13]
	global_load_dword v139, v[132:133], off
	v_lshl_add_u32 v152, v135, 4, s78
	v_and_b32_e32 v135, 63, v131
	v_cmp_eq_u32_e32 vcc, 0, v144
	v_or_b32_e32 v0, s97, v135
	v_lshrrev_b32_e32 v0, 1, v0
	v_and_or_b32 v131, v0, 63, s55
	v_add_u32_e32 v132, s15, v131
	v_ashrrev_i32_e32 v133, 31, v132
	v_lshlrev_b64 v[132:133], 6, v[132:133]
	v_lshl_add_u64 v[132:133], s[10:11], 0, v[132:133]
	v_lshlrev_b32_e32 v0, 5, v144
	v_lshl_add_u64 v[132:133], v[132:133], 0, v[0:1]
	global_load_dwordx4 v[148:151], v[132:133], off offset:16
	global_load_dwordx4 v[140:143], v[132:133], off
	s_waitcnt vmcnt(2)
	ds_write_b128 v152, v[136:139]
	s_waitcnt vmcnt(0)
	v_add_f32_e32 v133, v150, v151
	v_add_f32_e32 v0, v140, v141
	v_add_f32_e32 v132, v142, v143
	v_add_f32_e32 v0, v0, v132
	v_add_f32_e32 v132, v148, v149
	v_add_f32_e32 v132, v132, v133
	v_add_f32_e32 v0, v0, v132
	v_lshlrev_b32_e32 v132, 2, v135
	v_xor_b32_e32 v132, 4, v132
	ds_bpermute_b32 v132, v132, v0
	s_and_saveexec_b64 s[4:5], vcc
	s_cbranch_execz .LBB0_922
	s_waitcnt lgkmcnt(0)
	v_add_f32_e32 v0, v0, v132
	v_mov_b32_e32 v132, 0x358637bd
	v_fmamk_f32 v0, v0, 0x3a800000, v132
	s_mov_b32 s6, 0x800000
	v_mul_f32_e32 v132, 0x4b800000, v0
	v_cmp_gt_f32_e32 vcc, s6, v0
	v_lshl_add_u32 v131, v131, 2, 0
	v_add_u32_e32 v131, 0x20000, v131
	v_cndmask_b32_e32 v0, v0, v132, vcc
	v_rsq_f32_e32 v0, v0
	s_nop 0
	v_mul_f32_e32 v132, 0x45800000, v0
	v_cndmask_b32_e32 v0, v0, v132, vcc
	ds_write_b32 v131, v0

.LBB0_1090:
	v_lshl_add_u64 v[178:179], s[16:17], 0, v[196:197]
	s_add_i32 m0, s39, 0xc000
	ds_read_b128 v[146:149], v213
	ds_read_b128 v[150:153], v213 offset:1024
	ds_read_b128 v[154:157], v213 offset:2048
	ds_read_b128 v[158:161], v213 offset:3072
	ds_read_b128 v[162:165], v213 offset:4096
	ds_read_b128 v[166:169], v213 offset:5120
	ds_read_b128 v[170:173], v213 offset:6144
	ds_read_b128 v[174:177], v213 offset:7168
	global_load_lds_dwordx4 v[178:179], off
	s_add_i32 m0, s39, 0xe000
	v_lshl_add_u64 v[178:179], s[16:17], 0, v[198:199]
	global_load_lds_dwordx4 v[178:179], off
	s_waitcnt lgkmcnt(8)
	s_barrier
	s_waitcnt lgkmcnt(0)
	v_mfma_f32_16x16x32_bf16 v[126:129], v[130:133], v[146:149], v[126:129]
	v_mfma_f32_16x16x32_bf16 v[122:125], v[138:141], v[146:149], v[122:125]
	v_mfma_f32_16x16x32_bf16 v[110:113], v[130:133], v[154:157], v[110:113]
	v_mfma_f32_16x16x32_bf16 v[106:109], v[138:141], v[154:157], v[106:109]
	v_mfma_f32_16x16x32_bf16 v[94:97], v[130:133], v[162:165], v[94:97]
	v_mfma_f32_16x16x32_bf16 v[90:93], v[138:141], v[162:165], v[90:93]
	v_mfma_f32_16x16x32_bf16 v[78:81], v[130:133], v[170:173], v[78:81]
	v_mfma_f32_16x16x32_bf16 v[74:77], v[138:141], v[170:173], v[74:77]
	v_mfma_f32_16x16x32_bf16 v[126:129], v[134:137], v[150:153], v[126:129]
	v_mfma_f32_16x16x32_bf16 v[122:125], v[142:145], v[150:153], v[122:125]
	v_mfma_f32_16x16x32_bf16 v[110:113], v[134:137], v[158:161], v[110:113]
	v_mfma_f32_16x16x32_bf16 v[106:109], v[142:145], v[158:161], v[106:109]
	v_mfma_f32_16x16x32_bf16 v[94:97], v[134:137], v[166:169], v[94:97]
	v_mfma_f32_16x16x32_bf16 v[90:93], v[142:145], v[166:169], v[90:93]
	v_mfma_f32_16x16x32_bf16 v[78:81], v[134:137], v[174:177], v[78:81]
	v_mfma_f32_16x16x32_bf16 v[74:77], v[142:145], v[174:177], v[74:77]
	s_barrier
	s_add_i32 s91, 0, 0x14000
	v_add_u32_e32 v186, s91, v212
	s_add_i32 s16, s90, s38
	ds_read_b128 v[178:181], v186
	ds_read_b128 v[182:185], v186 offset:1024
	ds_read_b128 v[200:203], v186 offset:2048
	ds_read_b128 v[204:207], v186 offset:3072
	s_mov_b32 m0, s16
	global_load_lds_dwordx4 v0, s[86:87]
	s_add_i32 m0, s16, 0x2000
	s_nop 0
	global_load_lds_dwordx4 v194, s[86:87]
	s_barrier
	s_waitcnt lgkmcnt(0)
	v_mfma_f32_16x16x32_bf16 v[118:121], v[178:181], v[146:149], v[118:121]
	v_mfma_f32_16x16x32_bf16 v[114:117], v[200:203], v[146:149], v[114:117]
	v_mfma_f32_16x16x32_bf16 v[102:105], v[178:181], v[154:157], v[102:105]
	v_mfma_f32_16x16x32_bf16 v[98:101], v[200:203], v[154:157], v[98:101]
	v_mfma_f32_16x16x32_bf16 v[86:89], v[178:181], v[162:165], v[86:89]
	v_mfma_f32_16x16x32_bf16 v[82:85], v[200:203], v[162:165], v[82:85]
	v_mfma_f32_16x16x32_bf16 v[70:73], v[178:181], v[170:173], v[70:73]
	v_mfma_f32_16x16x32_bf16 v[66:69], v[200:203], v[170:173], v[66:69]
	v_mfma_f32_16x16x32_bf16 v[118:121], v[182:185], v[150:153], v[118:121]
	v_mfma_f32_16x16x32_bf16 v[114:117], v[204:207], v[150:153], v[114:117]
	v_mfma_f32_16x16x32_bf16 v[102:105], v[182:185], v[158:161], v[102:105]
	v_mfma_f32_16x16x32_bf16 v[98:101], v[204:207], v[158:161], v[98:101]
	v_mfma_f32_16x16x32_bf16 v[86:89], v[182:185], v[166:169], v[86:89]
	v_mfma_f32_16x16x32_bf16 v[82:85], v[204:207], v[166:169], v[82:85]
	v_mfma_f32_16x16x32_bf16 v[70:73], v[182:185], v[174:177], v[70:73]
	v_mfma_f32_16x16x32_bf16 v[66:69], v[204:207], v[174:177], v[66:69]
	s_mov_b32 m0, s39
	s_mov_b64 s[100:101], s[88:89]
	s_barrier
	ds_read_b128 v[146:149], v213 offset:16384
	ds_read_b128 v[150:153], v213 offset:17408
	ds_read_b128 v[154:157], v213 offset:18432
	ds_read_b128 v[158:161], v213 offset:19456
	ds_read_b128 v[162:165], v213 offset:20480
	ds_read_b128 v[166:169], v213 offset:21504
	ds_read_b128 v[170:173], v213 offset:22528
	ds_read_b128 v[174:177], v213 offset:23552
	global_load_lds_dwordx4 v190, s[100:101]
	s_mov_b32 m0, s42
	s_nop 0
	global_load_lds_dwordx4 v192, s[100:101]
	s_waitcnt vmcnt(10)
	s_barrier
	s_waitcnt lgkmcnt(0)
	v_mfma_f32_16x16x32_bf16 v[62:65], v[130:133], v[146:149], v[62:65]
	v_mfma_f32_16x16x32_bf16 v[58:61], v[138:141], v[146:149], v[58:61]
	v_mfma_f32_16x16x32_bf16 v[46:49], v[130:133], v[154:157], v[46:49]
	v_mfma_f32_16x16x32_bf16 v[42:45], v[138:141], v[154:157], v[42:45]
	v_mfma_f32_16x16x32_bf16 v[30:33], v[130:133], v[162:165], v[30:33]
	v_mfma_f32_16x16x32_bf16 v[26:29], v[138:141], v[162:165], v[26:29]
	v_mfma_f32_16x16x32_bf16 v[14:17], v[130:133], v[170:173], v[14:17]
	v_mfma_f32_16x16x32_bf16 v[10:13], v[138:141], v[170:173], v[10:13]
	v_mfma_f32_16x16x32_bf16 v[62:65], v[134:137], v[150:153], v[62:65]
	v_mfma_f32_16x16x32_bf16 v[58:61], v[142:145], v[150:153], v[58:61]
	v_mfma_f32_16x16x32_bf16 v[46:49], v[134:137], v[158:161], v[46:49]
	v_mfma_f32_16x16x32_bf16 v[42:45], v[142:145], v[158:161], v[42:45]
	v_mfma_f32_16x16x32_bf16 v[30:33], v[134:137], v[166:169], v[30:33]
	v_mfma_f32_16x16x32_bf16 v[26:29], v[142:145], v[166:169], v[26:29]
	v_mfma_f32_16x16x32_bf16 v[14:17], v[134:137], v[174:177], v[14:17]
	v_mfma_f32_16x16x32_bf16 v[10:13], v[142:145], v[174:177], v[10:13]
	s_barrier
	s_add_u32 s16, s86, 0xb0000
	s_addc_u32 s17, s87, 0
	s_add_i32 s90, s91, s38
	s_mov_b32 m0, s90
	s_nop 0
	global_load_lds_dwordx4 v0, s[16:17]
	s_add_i32 m0, s90, 0x2000
	s_nop 0
	global_load_lds_dwordx4 v194, s[16:17]
	s_add_i32 s90, 0, 0x18000
	v_add_u32_e32 v142, s90, v212
	ds_read_b128 v[130:133], v142
	ds_read_b128 v[134:137], v142 offset:1024
	ds_read_b128 v[138:141], v142 offset:2048
	ds_read_b128 v[142:145], v142 offset:3072
	s_waitcnt vmcnt(6)
	s_barrier
	v_mfma_f32_16x16x32_bf16 v[54:57], v[178:181], v[146:149], v[54:57]
	v_mfma_f32_16x16x32_bf16 v[50:53], v[200:203], v[146:149], v[50:53]
	v_mfma_f32_16x16x32_bf16 v[38:41], v[178:181], v[154:157], v[38:41]
	v_mfma_f32_16x16x32_bf16 v[34:37], v[200:203], v[154:157], v[34:37]
	v_mfma_f32_16x16x32_bf16 v[22:25], v[178:181], v[162:165], v[22:25]
	v_mfma_f32_16x16x32_bf16 v[18:21], v[200:203], v[162:165], v[18:21]
	v_mfma_f32_16x16x32_bf16 v[6:9], v[178:181], v[170:173], v[6:9]
	v_mfma_f32_16x16x32_bf16 v[2:5], v[200:203], v[170:173], v[2:5]
	v_mfma_f32_16x16x32_bf16 v[54:57], v[182:185], v[150:153], v[54:57]
	v_mfma_f32_16x16x32_bf16 v[50:53], v[204:207], v[150:153], v[50:53]
	v_mfma_f32_16x16x32_bf16 v[38:41], v[182:185], v[158:161], v[38:41]
	v_mfma_f32_16x16x32_bf16 v[34:37], v[204:207], v[158:161], v[34:37]
	v_mfma_f32_16x16x32_bf16 v[22:25], v[182:185], v[166:169], v[22:25]
	v_mfma_f32_16x16x32_bf16 v[18:21], v[204:207], v[166:169], v[18:21]
	v_mfma_f32_16x16x32_bf16 v[6:9], v[182:185], v[174:177], v[6:9]
	v_mfma_f32_16x16x32_bf16 v[2:5], v[204:207], v[174:177], v[2:5]
	s_barrier
	s_add_u32 s16, s88, 0xb0000
	s_addc_u32 s17, s89, 0
	s_mov_b32 m0, s43
	ds_read_b128 v[146:149], v213 offset:32768
	ds_read_b128 v[150:153], v213 offset:33792
	ds_read_b128 v[154:157], v213 offset:34816
	ds_read_b128 v[158:161], v213 offset:35840
	ds_read_b128 v[162:165], v213 offset:36864
	ds_read_b128 v[166:169], v213 offset:37888
	ds_read_b128 v[170:173], v213 offset:38912
	ds_read_b128 v[174:177], v213 offset:39936
	global_load_lds_dwordx4 v190, s[16:17]
	s_mov_b32 m0, s44
	s_nop 0
	global_load_lds_dwordx4 v192, s[16:17]
	s_waitcnt lgkmcnt(8)
	s_barrier
	s_waitcnt lgkmcnt(0)
	v_mfma_f32_16x16x32_bf16 v[126:129], v[130:133], v[146:149], v[126:129]
	v_mfma_f32_16x16x32_bf16 v[122:125], v[138:141], v[146:149], v[122:125]
	v_mfma_f32_16x16x32_bf16 v[110:113], v[130:133], v[154:157], v[110:113]
	v_mfma_f32_16x16x32_bf16 v[106:109], v[138:141], v[154:157], v[106:109]
	v_mfma_f32_16x16x32_bf16 v[94:97], v[130:133], v[162:165], v[94:97]
	v_mfma_f32_16x16x32_bf16 v[90:93], v[138:141], v[162:165], v[90:93]
	v_mfma_f32_16x16x32_bf16 v[78:81], v[130:133], v[170:173], v[78:81]
	v_mfma_f32_16x16x32_bf16 v[74:77], v[138:141], v[170:173], v[74:77]
	v_mfma_f32_16x16x32_bf16 v[126:129], v[134:137], v[150:153], v[126:129]
	v_mfma_f32_16x16x32_bf16 v[122:125], v[142:145], v[150:153], v[122:125]
	v_mfma_f32_16x16x32_bf16 v[110:113], v[134:137], v[158:161], v[110:113]
	v_mfma_f32_16x16x32_bf16 v[106:109], v[142:145], v[158:161], v[106:109]
	v_mfma_f32_16x16x32_bf16 v[94:97], v[134:137], v[166:169], v[94:97]
	v_mfma_f32_16x16x32_bf16 v[90:93], v[142:145], v[166:169], v[90:93]
	v_mfma_f32_16x16x32_bf16 v[78:81], v[134:137], v[174:177], v[78:81]
	v_mfma_f32_16x16x32_bf16 v[74:77], v[142:145], v[174:177], v[74:77]
	s_barrier
	s_add_i32 s88, 0, 0x1c000
	s_add_i32 s16, s90, s38
	v_add_u32_e32 v204, s88, v212
	s_mov_b32 m0, s16
	ds_read_b128 v[178:181], v204
	ds_read_b128 v[182:185], v204 offset:1024
	ds_read_b128 v[200:203], v204 offset:2048
	ds_read_b128 v[204:207], v204 offset:3072
	s_add_u32 s98, s86, s40
	s_addc_u32 s99, s87, s41
	global_load_lds_dwordx4 v0, s[98:99]
	s_add_i32 m0, s16, 0x2000
	s_add_u32 s98, s86, s40
	s_addc_u32 s99, s87, s41
	global_load_lds_dwordx4 v194, s[98:99]
	s_barrier
	s_waitcnt lgkmcnt(0)
	v_mfma_f32_16x16x32_bf16 v[118:121], v[178:181], v[146:149], v[118:121]
	v_mfma_f32_16x16x32_bf16 v[114:117], v[200:203], v[146:149], v[114:117]
	v_mfma_f32_16x16x32_bf16 v[102:105], v[178:181], v[154:157], v[102:105]
	v_mfma_f32_16x16x32_bf16 v[98:101], v[200:203], v[154:157], v[98:101]
	v_mfma_f32_16x16x32_bf16 v[86:89], v[178:181], v[162:165], v[86:89]
	v_mfma_f32_16x16x32_bf16 v[82:85], v[200:203], v[162:165], v[82:85]
	v_mfma_f32_16x16x32_bf16 v[70:73], v[178:181], v[170:173], v[70:73]
	v_mfma_f32_16x16x32_bf16 v[66:69], v[200:203], v[170:173], v[66:69]
	v_mfma_f32_16x16x32_bf16 v[118:121], v[182:185], v[150:153], v[118:121]
	v_mfma_f32_16x16x32_bf16 v[114:117], v[204:207], v[150:153], v[114:117]
	v_mfma_f32_16x16x32_bf16 v[102:105], v[182:185], v[158:161], v[102:105]
	v_mfma_f32_16x16x32_bf16 v[98:101], v[204:207], v[158:161], v[98:101]
	v_mfma_f32_16x16x32_bf16 v[86:89], v[182:185], v[166:169], v[86:89]
	v_mfma_f32_16x16x32_bf16 v[82:85], v[204:207], v[166:169], v[82:85]
	v_mfma_f32_16x16x32_bf16 v[70:73], v[182:185], v[174:177], v[70:73]
	v_mfma_f32_16x16x32_bf16 v[66:69], v[204:207], v[174:177], v[66:69]
	s_mov_b32 m0, s60
	s_barrier
	ds_read_b128 v[146:149], v213 offset:49152
	ds_read_b128 v[150:153], v213 offset:50176
	ds_read_b128 v[154:157], v213 offset:51200
	ds_read_b128 v[158:161], v213 offset:52224
	ds_read_b128 v[162:165], v213 offset:53248
	ds_read_b128 v[166:169], v213 offset:54272
	ds_read_b128 v[170:173], v213 offset:55296
	ds_read_b128 v[174:177], v213 offset:56320
	s_add_u32 s98, s100, s40
	s_addc_u32 s99, s101, s41
	global_load_lds_dwordx4 v190, s[98:99]
	s_mov_b32 m0, s61
	s_add_u32 s98, s100, s40
	s_addc_u32 s99, s101, s41
	global_load_lds_dwordx4 v192, s[98:99]
	s_waitcnt vmcnt(10)
	s_barrier
	s_waitcnt lgkmcnt(0)
	v_mfma_f32_16x16x32_bf16 v[62:65], v[130:133], v[146:149], v[62:65]
	v_mfma_f32_16x16x32_bf16 v[58:61], v[138:141], v[146:149], v[58:61]
	v_mfma_f32_16x16x32_bf16 v[46:49], v[130:133], v[154:157], v[46:49]
	v_mfma_f32_16x16x32_bf16 v[42:45], v[138:141], v[154:157], v[42:45]
	v_mfma_f32_16x16x32_bf16 v[30:33], v[130:133], v[162:165], v[30:33]
	v_mfma_f32_16x16x32_bf16 v[26:29], v[138:141], v[162:165], v[26:29]
	v_mfma_f32_16x16x32_bf16 v[14:17], v[130:133], v[170:173], v[14:17]
	v_mfma_f32_16x16x32_bf16 v[10:13], v[138:141], v[170:173], v[10:13]
	v_mfma_f32_16x16x32_bf16 v[62:65], v[134:137], v[150:153], v[62:65]
	v_mfma_f32_16x16x32_bf16 v[58:61], v[142:145], v[150:153], v[58:61]
	v_mfma_f32_16x16x32_bf16 v[46:49], v[134:137], v[158:161], v[46:49]
	v_mfma_f32_16x16x32_bf16 v[42:45], v[142:145], v[158:161], v[42:45]
	v_mfma_f32_16x16x32_bf16 v[30:33], v[134:137], v[166:169], v[30:33]
	v_mfma_f32_16x16x32_bf16 v[26:29], v[142:145], v[166:169], v[26:29]
	v_mfma_f32_16x16x32_bf16 v[14:17], v[134:137], v[174:177], v[14:17]
	v_mfma_f32_16x16x32_bf16 v[10:13], v[142:145], v[174:177], v[10:13]
	s_barrier
	s_add_u32 s16, s86, 0xb0080
	s_addc_u32 s17, s87, 0
	s_add_i32 s86, s88, s38
	s_mov_b32 m0, s86
	s_nop 0
	global_load_lds_dwordx4 v0, s[16:17]
	s_add_i32 m0, s86, 0x2000
	s_nop 0
	global_load_lds_dwordx4 v194, s[16:17]
	s_add_i32 s90, 0, 0x10000
	v_add_u32_e32 v142, s90, v212
	ds_read_b128 v[130:133], v142
	ds_read_b128 v[134:137], v142 offset:1024
	ds_read_b128 v[138:141], v142 offset:2048
	ds_read_b128 v[142:145], v142 offset:3072
	s_waitcnt vmcnt(6)
	s_barrier
	v_mfma_f32_16x16x32_bf16 v[54:57], v[178:181], v[146:149], v[54:57]
	v_mfma_f32_16x16x32_bf16 v[50:53], v[200:203], v[146:149], v[50:53]
	v_mfma_f32_16x16x32_bf16 v[38:41], v[178:181], v[154:157], v[38:41]
	v_mfma_f32_16x16x32_bf16 v[34:37], v[200:203], v[154:157], v[34:37]
	v_mfma_f32_16x16x32_bf16 v[22:25], v[178:181], v[162:165], v[22:25]
	v_mfma_f32_16x16x32_bf16 v[18:21], v[200:203], v[162:165], v[18:21]
	v_mfma_f32_16x16x32_bf16 v[6:9], v[178:181], v[170:173], v[6:9]
	v_mfma_f32_16x16x32_bf16 v[2:5], v[200:203], v[170:173], v[2:5]
	v_mfma_f32_16x16x32_bf16 v[54:57], v[182:185], v[150:153], v[54:57]
	v_mfma_f32_16x16x32_bf16 v[50:53], v[204:207], v[150:153], v[50:53]
	v_mfma_f32_16x16x32_bf16 v[38:41], v[182:185], v[158:161], v[38:41]
	v_mfma_f32_16x16x32_bf16 v[34:37], v[204:207], v[158:161], v[34:37]
	v_mfma_f32_16x16x32_bf16 v[22:25], v[182:185], v[166:169], v[22:25]
	v_mfma_f32_16x16x32_bf16 v[18:21], v[204:207], v[166:169], v[18:21]
	v_mfma_f32_16x16x32_bf16 v[6:9], v[182:185], v[174:177], v[6:9]
	v_mfma_f32_16x16x32_bf16 v[2:5], v[204:207], v[174:177], v[2:5]
	s_add_i32 s79, s79, 2
	s_add_u32 s34, s34, 0x100
	s_addc_u32 s78, s78, 0
	s_mov_b64 s[16:17], s[84:85]
	s_add_u32 s84, s16, 0x100
	s_addc_u32 s85, s17, 0
	s_cmp_eq_u32 s79, 40
	s_cselect_b32 s89, s5, s85
	s_cselect_b32 s88, s4, s84
	s_cselect_b32 s87, s7, s78
	s_cselect_b32 s86, s6, s34
	s_cmp_gt_u32 s79, 41
	s_barrier
	s_cbranch_scc0 .LBB0_1090
	s_waitcnt lgkmcnt(0)
	s_lshl_b32 s16, s23, 8
	v_mov_b32_e32 v186, v252
	s_add_i32 s16, s16, s47
	s_nop 0
	v_and_or_b32 v202, v186, 15, s16
	s_lshl_b32 s16, s22, 8
	s_or_b32 s16, s16, s55
	v_lshrrev_b32_e32 v130, 1, v186
	v_and_or_b32 v200, v130, 24, s16
	v_ashrrev_i32_e32 v201, 31, v200
	v_ashrrev_i32_e32 v203, 31, v202
	v_lshl_add_u64 v[204:205], v[200:201], 2, s[12:13]
	v_lshlrev_b64 v[130:131], 12, v[202:203]
	v_lshl_add_u64 v[130:131], v[204:205], 0, v[130:131]
	global_load_dwordx4 v[216:219], v[130:131], off offset:16
	global_load_dwordx4 v[220:223], v[130:131], off
	global_load_dwordx4 v[178:181], v[130:131], off offset:528
	global_load_dwordx4 v[182:185], v[130:131], off offset:512
	v_or_b32_e32 v210, 16, v202
	v_ashrrev_i32_e32 v211, 31, v210
	v_lshlrev_b64 v[130:131], 12, v[210:211]
	v_or_b32_e32 v208, 32, v202
	v_lshl_add_u64 v[130:131], v[204:205], 0, v[130:131]
	v_ashrrev_i32_e32 v209, 31, v208
	global_load_dwordx4 v[170:173], v[130:131], off offset:16
	global_load_dwordx4 v[174:177], v[130:131], off
	global_load_dwordx4 v[162:165], v[130:131], off offset:528
	global_load_dwordx4 v[166:169], v[130:131], off offset:512
	v_lshlrev_b64 v[130:131], 12, v[208:209]
	v_or_b32_e32 v206, 48, v202
	v_lshl_add_u64 v[130:131], v[204:205], 0, v[130:131]
	v_ashrrev_i32_e32 v207, 31, v206
	global_load_dwordx4 v[154:157], v[130:131], off offset:16
	global_load_dwordx4 v[158:161], v[130:131], off
	global_load_dwordx4 v[138:141], v[130:131], off offset:528
	global_load_dwordx4 v[142:145], v[130:131], off offset:512
	v_lshlrev_b64 v[130:131], 12, v[206:207]
	v_lshl_add_u64 v[134:135], v[204:205], 0, v[130:131]
	global_load_dwordx4 v[146:149], v[134:135], off offset:16
	global_load_dwordx4 v[150:153], v[134:135], off
	global_load_dwordx4 v[130:133], v[134:135], off offset:528
	s_nop 0
	global_load_dwordx4 v[134:137], v[134:135], off offset:512
	v_and_b32_e32 v186, 63, v186
	v_lshlrev_b32_e32 v187, 2, v186
	v_xor_b32_e32 v215, 64, v187
	v_xor_b32_e32 v214, 0x80, v187
	v_cmp_gt_u32_e32 vcc, 16, v186
	v_lshlrev_b64 v[186:187], 10, v[202:203]
	v_lshl_add_u64 v[186:187], v[186:187], 0, v[200:201]
	s_lshl_b32 s16, s22, 2
	s_ashr_i32 s17, s16, 31
	s_waitcnt vmcnt(0)
	v_pk_add_f32 v[124:125], v[124:125], v[218:219]
	v_pk_add_f32 v[128:129], v[128:129], v[222:223]
	v_pk_add_f32 v[126:127], v[126:127], v[220:221]
	v_pk_mul_f32 v[218:219], v[128:129], v[128:129]
	v_pk_mul_f32 v[220:221], v[126:127], v[126:127]
	v_pk_add_f32 v[122:123], v[122:123], v[216:217]
	v_lshl_add_u64 v[216:217], v[186:187], 2, s[14:15]
	v_add_f32_e32 v220, v220, v221
	v_add_f32_e32 v218, v218, v219
	global_store_dwordx4 v[216:217], v[126:129], off
	global_store_dwordx4 v[216:217], v[122:125], off offset:16
	v_add_f32_e32 v222, v220, v218
	v_pk_mul_f32 v[220:221], v[122:123], v[122:123]
	v_cvt_pk_bf16_f32 v126, v126, v127
	v_cvt_pk_bf16_f32 v127, v128, v129
	v_cvt_pk_bf16_f32 v128, v122, v123
	v_cvt_pk_bf16_f32 v129, v124, v125
	v_lshl_add_u64 v[122:123], v[186:187], 1, s[80:81]
	v_pk_add_f32 v[120:121], v[120:121], v[184:185]
	v_pk_add_f32 v[118:119], v[118:119], v[182:183]
	v_pk_mul_f32 v[218:219], v[124:125], v[124:125]
	global_store_dwordx4 v[122:123], v[126:129], off
	v_pk_mul_f32 v[124:125], v[120:121], v[120:121]
	v_pk_add_f32 v[116:117], v[116:117], v[180:181]
	v_pk_mul_f32 v[126:127], v[118:119], v[118:119]
	v_pk_add_f32 v[114:115], v[114:115], v[178:179]
	v_add_f32_e32 v126, v126, v127
	v_add_f32_e32 v124, v124, v125
	v_add_f32_e32 v128, v126, v124
	v_pk_mul_f32 v[124:125], v[116:117], v[116:117]
	v_pk_mul_f32 v[126:127], v[114:115], v[114:115]
	v_add_f32_e32 v220, v220, v221
	v_add_f32_e32 v218, v218, v219
	v_add_f32_e32 v126, v126, v127
	v_add_f32_e32 v124, v124, v125
	v_add_f32_e32 v218, v220, v218
	v_add_f32_e32 v124, v126, v124
	v_add_f32_e32 v218, v222, v218
	v_add_f32_e32 v124, v128, v124
	v_add_f32_e32 v124, v218, v124
	global_store_dwordx4 v[216:217], v[118:121], off offset:512
	global_store_dwordx4 v[216:217], v[114:117], off offset:528
	s_nop 0
	v_cvt_pk_bf16_f32 v118, v118, v119
	v_cvt_pk_bf16_f32 v119, v120, v121
	v_cvt_pk_bf16_f32 v120, v114, v115
	ds_bpermute_b32 v114, v215, v124
	v_cvt_pk_bf16_f32 v121, v116, v117
	global_store_dwordx4 v[122:123], v[118:121], off offset:256
	s_waitcnt lgkmcnt(0)
	v_add_f32_e32 v114, v124, v114
	ds_bpermute_b32 v115, v214, v114
	s_and_saveexec_b64 s[22:23], vcc
	s_cbranch_execz .LBB0_1093
	v_lshlrev_b64 v[116:117], 6, v[202:203]
	v_lshl_add_u64 v[116:117], s[82:83], 0, v[116:117]
	v_lshl_add_u64 v[116:117], s[16:17], 2, v[116:117]
	s_lshl_b32 s34, s45, 2
	v_lshl_add_u64 v[116:117], v[116:117], 0, s[34:35]
	s_waitcnt lgkmcnt(0)
	v_add_f32_e32 v114, v114, v115
	global_store_dword v[116:117], v114, off

.LBB0_1209:
	s_waitcnt lgkmcnt(0)
	s_add_i32 m0, s39, 0xc000
	ds_read_b128 v[158:161], v171
	ds_read_b128 v[162:165], v171 offset:1024
	ds_read_b128 v[166:169], v171 offset:2048
	ds_read_b128 v[172:175], v171 offset:3072
	ds_read_b128 v[176:179], v171 offset:4096
	ds_read_b128 v[180:183], v171 offset:5120
	ds_read_b128 v[184:187], v171 offset:6144
	ds_read_b128 v[190:193], v171 offset:7168
	global_load_lds_dwordx4 v154, s[88:89]
	s_add_i32 m0, s39, 0xe000
	s_nop 0
	global_load_lds_dwordx4 v156, s[88:89]
	s_waitcnt lgkmcnt(8)
	s_barrier
	s_waitcnt lgkmcnt(0)
	v_mfma_f32_16x16x32_bf16 v[126:129], v[130:133], v[158:161], v[126:129]
	v_mfma_f32_16x16x32_bf16 v[122:125], v[138:141], v[158:161], v[122:125]
	v_mfma_f32_16x16x32_bf16 v[110:113], v[130:133], v[166:169], v[110:113]
	v_mfma_f32_16x16x32_bf16 v[106:109], v[138:141], v[166:169], v[106:109]
	v_mfma_f32_16x16x32_bf16 v[94:97], v[130:133], v[176:179], v[94:97]
	v_mfma_f32_16x16x32_bf16 v[90:93], v[138:141], v[176:179], v[90:93]
	v_mfma_f32_16x16x32_bf16 v[78:81], v[130:133], v[184:187], v[78:81]
	v_mfma_f32_16x16x32_bf16 v[74:77], v[138:141], v[184:187], v[74:77]
	v_mfma_f32_16x16x32_bf16 v[126:129], v[134:137], v[162:165], v[126:129]
	v_mfma_f32_16x16x32_bf16 v[122:125], v[142:145], v[162:165], v[122:125]
	v_mfma_f32_16x16x32_bf16 v[110:113], v[134:137], v[172:175], v[110:113]
	v_mfma_f32_16x16x32_bf16 v[106:109], v[142:145], v[172:175], v[106:109]
	v_mfma_f32_16x16x32_bf16 v[94:97], v[134:137], v[180:183], v[94:97]
	v_mfma_f32_16x16x32_bf16 v[90:93], v[142:145], v[180:183], v[90:93]
	v_mfma_f32_16x16x32_bf16 v[78:81], v[134:137], v[190:193], v[78:81]
	v_mfma_f32_16x16x32_bf16 v[74:77], v[142:145], v[190:193], v[74:77]
	s_barrier
	s_add_i32 s87, 0, 0x14000
	s_add_i32 s94, s94, s38
	v_add_u32_e32 v0, s87, v170
	s_mov_b32 m0, s94
	ds_read_b128 v[194:197], v0
	ds_read_b128 v[198:201], v0 offset:1024
	ds_read_b128 v[202:205], v0 offset:2048
	ds_read_b128 v[206:209], v0 offset:3072
	global_load_lds_dwordx4 v148, s[90:91]
	s_add_i32 m0, s94, 0x2000
	s_nop 0
	global_load_lds_dwordx4 v152, s[90:91]
	s_barrier
	s_waitcnt lgkmcnt(0)
	v_mfma_f32_16x16x32_bf16 v[118:121], v[194:197], v[158:161], v[118:121]
	v_mfma_f32_16x16x32_bf16 v[114:117], v[202:205], v[158:161], v[114:117]
	v_mfma_f32_16x16x32_bf16 v[102:105], v[194:197], v[166:169], v[102:105]
	v_mfma_f32_16x16x32_bf16 v[98:101], v[202:205], v[166:169], v[98:101]
	v_mfma_f32_16x16x32_bf16 v[86:89], v[194:197], v[176:179], v[86:89]
	v_mfma_f32_16x16x32_bf16 v[82:85], v[202:205], v[176:179], v[82:85]
	v_mfma_f32_16x16x32_bf16 v[70:73], v[194:197], v[184:187], v[70:73]
	v_mfma_f32_16x16x32_bf16 v[66:69], v[202:205], v[184:187], v[66:69]
	v_mfma_f32_16x16x32_bf16 v[118:121], v[198:201], v[162:165], v[118:121]
	v_mfma_f32_16x16x32_bf16 v[114:117], v[206:209], v[162:165], v[114:117]
	v_mfma_f32_16x16x32_bf16 v[102:105], v[198:201], v[172:175], v[102:105]
	v_mfma_f32_16x16x32_bf16 v[98:101], v[206:209], v[172:175], v[98:101]
	v_mfma_f32_16x16x32_bf16 v[86:89], v[198:201], v[180:183], v[86:89]
	v_mfma_f32_16x16x32_bf16 v[82:85], v[206:209], v[180:183], v[82:85]
	v_mfma_f32_16x16x32_bf16 v[70:73], v[198:201], v[190:193], v[70:73]
	v_mfma_f32_16x16x32_bf16 v[66:69], v[206:209], v[190:193], v[66:69]
	s_mov_b32 m0, s39
	s_mov_b64 s[100:101], s[92:93]
	s_barrier
	ds_read_b128 v[158:161], v171 offset:16384
	ds_read_b128 v[162:165], v171 offset:17408
	ds_read_b128 v[166:169], v171 offset:18432
	ds_read_b128 v[172:175], v171 offset:19456
	ds_read_b128 v[176:179], v171 offset:20480
	ds_read_b128 v[180:183], v171 offset:21504
	ds_read_b128 v[184:187], v171 offset:22528
	ds_read_b128 v[190:193], v171 offset:23552
	global_load_lds_dwordx4 v146, s[100:101]
	s_mov_b32 m0, s42
	s_nop 0
	global_load_lds_dwordx4 v150, s[100:101]
	s_waitcnt vmcnt(10)
	s_barrier
	s_waitcnt lgkmcnt(0)
	v_mfma_f32_16x16x32_bf16 v[62:65], v[130:133], v[158:161], v[62:65]
	v_mfma_f32_16x16x32_bf16 v[58:61], v[138:141], v[158:161], v[58:61]
	v_mfma_f32_16x16x32_bf16 v[46:49], v[130:133], v[166:169], v[46:49]
	v_mfma_f32_16x16x32_bf16 v[42:45], v[138:141], v[166:169], v[42:45]
	v_mfma_f32_16x16x32_bf16 v[30:33], v[130:133], v[176:179], v[30:33]
	v_mfma_f32_16x16x32_bf16 v[26:29], v[138:141], v[176:179], v[26:29]
	v_mfma_f32_16x16x32_bf16 v[14:17], v[130:133], v[184:187], v[14:17]
	v_mfma_f32_16x16x32_bf16 v[10:13], v[138:141], v[184:187], v[10:13]
	v_mfma_f32_16x16x32_bf16 v[62:65], v[134:137], v[162:165], v[62:65]
	v_mfma_f32_16x16x32_bf16 v[58:61], v[142:145], v[162:165], v[58:61]
	v_mfma_f32_16x16x32_bf16 v[46:49], v[134:137], v[172:175], v[46:49]
	v_mfma_f32_16x16x32_bf16 v[42:45], v[142:145], v[172:175], v[42:45]
	v_mfma_f32_16x16x32_bf16 v[30:33], v[134:137], v[180:183], v[30:33]
	v_mfma_f32_16x16x32_bf16 v[26:29], v[142:145], v[180:183], v[26:29]
	v_mfma_f32_16x16x32_bf16 v[14:17], v[134:137], v[190:193], v[14:17]
	v_mfma_f32_16x16x32_bf16 v[10:13], v[142:145], v[190:193], v[10:13]
	s_barrier
	s_add_u32 s94, s90, 0x40000
	s_addc_u32 s95, s91, 0
	s_add_i32 s87, s87, s38
	s_mov_b32 m0, s87
	s_nop 0
	global_load_lds_dwordx4 v148, s[94:95]
	s_add_i32 m0, s87, 0x2000
	s_nop 0
	global_load_lds_dwordx4 v152, s[94:95]
	s_add_i32 s87, 0, 0x18000
	v_add_u32_e32 v0, s87, v170
	ds_read_b128 v[130:133], v0
	ds_read_b128 v[134:137], v0 offset:1024
	ds_read_b128 v[138:141], v0 offset:2048
	ds_read_b128 v[142:145], v0 offset:3072
	s_waitcnt vmcnt(6)
	s_barrier
	v_mfma_f32_16x16x32_bf16 v[54:57], v[194:197], v[158:161], v[54:57]
	v_mfma_f32_16x16x32_bf16 v[50:53], v[202:205], v[158:161], v[50:53]
	v_mfma_f32_16x16x32_bf16 v[38:41], v[194:197], v[166:169], v[38:41]
	v_mfma_f32_16x16x32_bf16 v[34:37], v[202:205], v[166:169], v[34:37]
	v_mfma_f32_16x16x32_bf16 v[22:25], v[194:197], v[176:179], v[22:25]
	v_mfma_f32_16x16x32_bf16 v[18:21], v[202:205], v[176:179], v[18:21]
	v_mfma_f32_16x16x32_bf16 v[6:9], v[194:197], v[184:187], v[6:9]
	v_mfma_f32_16x16x32_bf16 v[2:5], v[202:205], v[184:187], v[2:5]
	v_mfma_f32_16x16x32_bf16 v[54:57], v[198:201], v[162:165], v[54:57]
	v_mfma_f32_16x16x32_bf16 v[50:53], v[206:209], v[162:165], v[50:53]
	v_mfma_f32_16x16x32_bf16 v[38:41], v[198:201], v[172:175], v[38:41]
	v_mfma_f32_16x16x32_bf16 v[34:37], v[206:209], v[172:175], v[34:37]
	v_mfma_f32_16x16x32_bf16 v[22:25], v[198:201], v[180:183], v[22:25]
	v_mfma_f32_16x16x32_bf16 v[18:21], v[206:209], v[180:183], v[18:21]
	v_mfma_f32_16x16x32_bf16 v[6:9], v[198:201], v[190:193], v[6:9]
	v_mfma_f32_16x16x32_bf16 v[2:5], v[206:209], v[190:193], v[2:5]
	s_barrier
	s_add_u32 s92, s92, 0x40000
	s_addc_u32 s93, s93, 0
	s_mov_b32 m0, s43
	ds_read_b128 v[158:161], v171 offset:32768
	ds_read_b128 v[162:165], v171 offset:33792
	ds_read_b128 v[166:169], v171 offset:34816
	ds_read_b128 v[172:175], v171 offset:35840
	ds_read_b128 v[176:179], v171 offset:36864
	ds_read_b128 v[180:183], v171 offset:37888
	ds_read_b128 v[184:187], v171 offset:38912
	ds_read_b128 v[190:193], v171 offset:39936
	global_load_lds_dwordx4 v146, s[92:93]
	s_mov_b32 m0, s44
	s_nop 0
	global_load_lds_dwordx4 v150, s[92:93]
	s_waitcnt lgkmcnt(8)
	s_barrier
	s_waitcnt lgkmcnt(0)
	v_mfma_f32_16x16x32_bf16 v[126:129], v[130:133], v[158:161], v[126:129]
	v_mfma_f32_16x16x32_bf16 v[122:125], v[138:141], v[158:161], v[122:125]
	v_mfma_f32_16x16x32_bf16 v[110:113], v[130:133], v[166:169], v[110:113]
	v_mfma_f32_16x16x32_bf16 v[106:109], v[138:141], v[166:169], v[106:109]
	v_mfma_f32_16x16x32_bf16 v[94:97], v[130:133], v[176:179], v[94:97]
	v_mfma_f32_16x16x32_bf16 v[90:93], v[138:141], v[176:179], v[90:93]
	v_mfma_f32_16x16x32_bf16 v[78:81], v[130:133], v[184:187], v[78:81]
	v_mfma_f32_16x16x32_bf16 v[74:77], v[138:141], v[184:187], v[74:77]
	v_mfma_f32_16x16x32_bf16 v[126:129], v[134:137], v[162:165], v[126:129]
	v_mfma_f32_16x16x32_bf16 v[122:125], v[142:145], v[162:165], v[122:125]
	v_mfma_f32_16x16x32_bf16 v[110:113], v[134:137], v[172:175], v[110:113]
	v_mfma_f32_16x16x32_bf16 v[106:109], v[142:145], v[172:175], v[106:109]
	v_mfma_f32_16x16x32_bf16 v[94:97], v[134:137], v[180:183], v[94:97]
	v_mfma_f32_16x16x32_bf16 v[90:93], v[142:145], v[180:183], v[90:93]
	v_mfma_f32_16x16x32_bf16 v[78:81], v[134:137], v[190:193], v[78:81]
	v_mfma_f32_16x16x32_bf16 v[74:77], v[142:145], v[190:193], v[74:77]
	s_barrier
	s_add_i32 s92, 0, 0x1c000
	s_add_i32 s87, s87, s38
	v_add_u32_e32 v0, s92, v170
	s_mov_b32 m0, s87
	ds_read_b128 v[194:197], v0
	ds_read_b128 v[198:201], v0 offset:1024
	ds_read_b128 v[202:205], v0 offset:2048
	ds_read_b128 v[206:209], v0 offset:3072
	s_add_u32 s98, s90, s40
	s_addc_u32 s99, s91, s41
	global_load_lds_dwordx4 v148, s[98:99]
	s_add_i32 m0, s87, 0x2000
	s_add_u32 s98, s90, s40
	s_addc_u32 s99, s91, s41
	global_load_lds_dwordx4 v152, s[98:99]
	s_barrier
	s_waitcnt lgkmcnt(0)
	v_mfma_f32_16x16x32_bf16 v[118:121], v[194:197], v[158:161], v[118:121]
	v_mfma_f32_16x16x32_bf16 v[114:117], v[202:205], v[158:161], v[114:117]
	v_mfma_f32_16x16x32_bf16 v[102:105], v[194:197], v[166:169], v[102:105]
	v_mfma_f32_16x16x32_bf16 v[98:101], v[202:205], v[166:169], v[98:101]
	v_mfma_f32_16x16x32_bf16 v[86:89], v[194:197], v[176:179], v[86:89]
	v_mfma_f32_16x16x32_bf16 v[82:85], v[202:205], v[176:179], v[82:85]
	v_mfma_f32_16x16x32_bf16 v[70:73], v[194:197], v[184:187], v[70:73]
	v_mfma_f32_16x16x32_bf16 v[66:69], v[202:205], v[184:187], v[66:69]
	v_mfma_f32_16x16x32_bf16 v[118:121], v[198:201], v[162:165], v[118:121]
	v_mfma_f32_16x16x32_bf16 v[114:117], v[206:209], v[162:165], v[114:117]
	v_mfma_f32_16x16x32_bf16 v[102:105], v[198:201], v[172:175], v[102:105]
	v_mfma_f32_16x16x32_bf16 v[98:101], v[206:209], v[172:175], v[98:101]
	v_mfma_f32_16x16x32_bf16 v[86:89], v[198:201], v[180:183], v[86:89]
	v_mfma_f32_16x16x32_bf16 v[82:85], v[206:209], v[180:183], v[82:85]
	v_mfma_f32_16x16x32_bf16 v[70:73], v[198:201], v[190:193], v[70:73]
	v_mfma_f32_16x16x32_bf16 v[66:69], v[206:209], v[190:193], v[66:69]
	s_mov_b32 m0, s60
	s_barrier
	ds_read_b128 v[158:161], v171 offset:49152
	ds_read_b128 v[162:165], v171 offset:50176
	ds_read_b128 v[166:169], v171 offset:51200
	ds_read_b128 v[172:175], v171 offset:52224
	ds_read_b128 v[176:179], v171 offset:53248
	ds_read_b128 v[180:183], v171 offset:54272
	ds_read_b128 v[184:187], v171 offset:55296
	ds_read_b128 v[190:193], v171 offset:56320
	s_add_u32 s98, s100, s40
	s_addc_u32 s99, s101, s41
	global_load_lds_dwordx4 v146, s[98:99]
	s_mov_b32 m0, s61
	s_add_u32 s98, s100, s40
	s_addc_u32 s99, s101, s41
	global_load_lds_dwordx4 v150, s[98:99]
	s_waitcnt vmcnt(10)
	s_barrier
	s_waitcnt lgkmcnt(0)
	v_mfma_f32_16x16x32_bf16 v[62:65], v[130:133], v[158:161], v[62:65]
	v_mfma_f32_16x16x32_bf16 v[58:61], v[138:141], v[158:161], v[58:61]
	v_mfma_f32_16x16x32_bf16 v[46:49], v[130:133], v[166:169], v[46:49]
	v_mfma_f32_16x16x32_bf16 v[42:45], v[138:141], v[166:169], v[42:45]
	v_mfma_f32_16x16x32_bf16 v[30:33], v[130:133], v[176:179], v[30:33]
	v_mfma_f32_16x16x32_bf16 v[26:29], v[138:141], v[176:179], v[26:29]
	v_mfma_f32_16x16x32_bf16 v[14:17], v[130:133], v[184:187], v[14:17]
	v_mfma_f32_16x16x32_bf16 v[10:13], v[138:141], v[184:187], v[10:13]
	v_mfma_f32_16x16x32_bf16 v[62:65], v[134:137], v[162:165], v[62:65]
	v_mfma_f32_16x16x32_bf16 v[58:61], v[142:145], v[162:165], v[58:61]
	v_mfma_f32_16x16x32_bf16 v[46:49], v[134:137], v[172:175], v[46:49]
	v_mfma_f32_16x16x32_bf16 v[42:45], v[142:145], v[172:175], v[42:45]
	v_mfma_f32_16x16x32_bf16 v[30:33], v[134:137], v[180:183], v[30:33]
	v_mfma_f32_16x16x32_bf16 v[26:29], v[142:145], v[180:183], v[26:29]
	v_mfma_f32_16x16x32_bf16 v[14:17], v[134:137], v[190:193], v[14:17]
	v_mfma_f32_16x16x32_bf16 v[10:13], v[142:145], v[190:193], v[10:13]
	s_barrier
	s_add_u32 s90, s90, 0x40080
	s_addc_u32 s91, s91, 0
	s_add_i32 s87, s92, s38
	s_mov_b32 m0, s87
	s_nop 0
	global_load_lds_dwordx4 v148, s[90:91]
	s_add_i32 m0, s87, 0x2000
	s_nop 0
	global_load_lds_dwordx4 v152, s[90:91]
	s_add_i32 s94, 0, 0x10000
	v_add_u32_e32 v0, s94, v170
	ds_read_b128 v[130:133], v0
	ds_read_b128 v[134:137], v0 offset:1024
	ds_read_b128 v[138:141], v0 offset:2048
	ds_read_b128 v[142:145], v0 offset:3072
	s_waitcnt vmcnt(6)
	s_barrier
	v_mfma_f32_16x16x32_bf16 v[54:57], v[194:197], v[158:161], v[54:57]
	v_mfma_f32_16x16x32_bf16 v[50:53], v[202:205], v[158:161], v[50:53]
	v_mfma_f32_16x16x32_bf16 v[38:41], v[194:197], v[166:169], v[38:41]
	v_mfma_f32_16x16x32_bf16 v[34:37], v[202:205], v[166:169], v[34:37]
	v_mfma_f32_16x16x32_bf16 v[22:25], v[194:197], v[176:179], v[22:25]
	v_mfma_f32_16x16x32_bf16 v[18:21], v[202:205], v[176:179], v[18:21]
	v_mfma_f32_16x16x32_bf16 v[6:9], v[194:197], v[184:187], v[6:9]
	v_mfma_f32_16x16x32_bf16 v[2:5], v[202:205], v[184:187], v[2:5]
	v_mfma_f32_16x16x32_bf16 v[54:57], v[198:201], v[162:165], v[54:57]
	v_mfma_f32_16x16x32_bf16 v[50:53], v[206:209], v[162:165], v[50:53]
	v_mfma_f32_16x16x32_bf16 v[38:41], v[198:201], v[172:175], v[38:41]
	v_mfma_f32_16x16x32_bf16 v[34:37], v[206:209], v[172:175], v[34:37]
	v_mfma_f32_16x16x32_bf16 v[22:25], v[198:201], v[180:183], v[22:25]
	v_mfma_f32_16x16x32_bf16 v[18:21], v[206:209], v[180:183], v[18:21]
	v_mfma_f32_16x16x32_bf16 v[6:9], v[198:201], v[190:193], v[6:9]
	v_mfma_f32_16x16x32_bf16 v[2:5], v[206:209], v[190:193], v[2:5]
	s_add_i32 s85, s85, 2
	s_add_u32 s88, s88, 0x100
	s_addc_u32 s89, s89, 0
	s_add_u32 s34, s34, 0x100
	s_addc_u32 s79, s79, 0
	s_add_u32 s87, s88, 0xfffc0080
	s_addc_u32 s90, s89, -1
	s_cmp_eq_u32 s85, 12
	s_cselect_b32 s93, s13, s90
	s_cselect_b32 s92, s22, s87
	s_cselect_b32 s91, s7, s79
	s_cselect_b32 s90, s23, s34
	s_cmp_gt_u32 s85, 13
	s_barrier
	s_cbranch_scc0 .LBB0_1209
	s_waitcnt lgkmcnt(0)
	v_mov_b32_e32 v131, v252
	s_lshl_b32 s7, s86, 8
	v_and_b32_e32 v130, 63, v131
	v_or_b32_e32 v0, s72, v130
	v_lshrrev_b32_e32 v0, 1, v0
	v_and_or_b32 v132, v0, 63, s73
	v_add_u32_e32 v134, s7, v132
	v_ashrrev_i32_e32 v135, 31, v134
	v_and_b32_e32 v142, 1, v131
	v_lshlrev_b64 v[134:135], 6, v[134:135]
	v_lshl_add_u64 v[134:135], s[82:83], 0, v[134:135]
	v_lshlrev_b32_e32 v0, 5, v142
	v_lshl_add_u64 v[138:139], v[134:135], 0, v[0:1]
	global_load_dwordx4 v[134:137], v[138:139], off
	s_nop 0
	global_load_dwordx4 v[138:141], v[138:139], off offset:16
	v_lshlrev_b32_e32 v0, 2, v130
	v_cmp_eq_u32_e32 vcc, 0, v142
	s_waitcnt vmcnt(0)
	v_add_f32_e32 v133, v134, v135
	v_add_f32_e32 v134, v136, v137
	v_add_f32_e32 v135, v138, v139
	v_add_f32_e32 v136, v140, v141
	v_add_f32_e32 v133, v133, v134
	v_add_f32_e32 v134, v135, v136
	v_add_f32_e32 v133, v133, v134
	v_xor_b32_e32 v134, 4, v0
	ds_bpermute_b32 v134, v134, v133
	s_and_saveexec_b64 s[22:23], vcc
	s_cbranch_execz .LBB0_1212
	s_waitcnt lgkmcnt(0)
	v_add_f32_e32 v133, v133, v134
	v_fmamk_f32 v133, v133, 0x3a800000, v224
	s_mov_b32 s13, 0x800000
	v_mul_f32_e32 v134, 0x4b800000, v133
	v_cmp_gt_f32_e32 vcc, s13, v133
	v_lshl_add_u32 v132, v132, 2, 0
	v_add_u32_e32 v132, 0x20000, v132
	v_cndmask_b32_e32 v133, v133, v134, vcc
	v_rsq_f32_e32 v133, v133
	s_nop 0
	v_mul_f32_e32 v134, 0x45800000, v133
	v_cndmask_b32_e32 v133, v133, v134, vcc
	ds_write_b32 v132, v133
